# c4: norms + early K-loop barrier + attention staging unrolled + HGRN fold loads batched + early acquire-invalidate in group barriers
# speedup vs baseline: 1.0072x; 1.0026x over previous
.LBB0_389:
	s_or_b64 exec, exec, s[8:9]
	v_mov_b32_e32 v1, 0
	global_load_dword v4, v1, s[4:5] sc1
	buffer_inv sc1
	s_waitcnt vmcnt(2)
	v_readfirstlane_b32 s6, v3
	s_nop 1
	v_add_u32_e32 v2, s6, v2
	v_and_b32_e32 v2, -4, v2
	v_add_u32_e32 v2, 4, v2
	s_waitcnt vmcnt(1)
	v_cmp_lt_u32_e32 vcc, v4, v2
	s_and_saveexec_b64 s[6:7], vcc
	s_cbranch_execz .LBB0_402
	s_mov_b32 s18, 1
	s_mov_b64 s[8:9], 0
	s_branch .LBB0_392

.LBB0_402:
	s_or_b64 exec, exec, s[6:7]
	s_waitcnt vmcnt(0)
	s_waitcnt vmcnt(0)
	s_branch .LBB0_454

.LBB0_963:
	s_ashr_i32 s67, s66, 31
	s_lshl_b64 s[76:77], s[66:67], 12
	s_ashr_i32 s65, s64, 31
	v_lshl_add_u64 v[100:101], v[178:179], 0, s[76:77]
	s_lshl_b64 s[76:77], s[64:65], 9
	v_lshl_add_u64 v[98:99], v[182:183], 0, s[76:77]
	s_mov_b64 s[76:77], 0x1000
	v_lshl_add_u64 v[238:239], v[100:101], 0, s[76:77]
	s_mov_b64 s[76:77], 0x3000
	v_lshl_add_u64 v[240:241], v[100:101], 0, s[76:77]
	global_load_dwordx4 v[102:105], v[238:239], off offset:-4096
	global_load_dwordx4 v[108:111], v[238:239], off offset:-4080
	global_load_dwordx4 v[112:115], v[238:239], off offset:-4064
	global_load_dwordx4 v[116:119], v[238:239], off offset:-4048
	global_load_dwordx4 v[120:123], v[98:99], off
	global_load_dwordx4 v[124:127], v[98:99], off offset:32
	global_load_dwordx4 v[128:131], v[98:99], off offset:64
	global_load_dwordx4 v[132:135], v[98:99], off offset:96
	global_load_dwordx4 v[138:141], v[238:239], off
	global_load_dwordx4 v[142:145], v[238:239], off offset:16
	global_load_dwordx4 v[146:149], v[238:239], off offset:32
	global_load_dwordx4 v[150:153], v[238:239], off offset:48
	global_load_dwordx4 v[154:157], v[98:99], off offset:128
	global_load_dwordx4 v[158:161], v[98:99], off offset:160
	global_load_dwordx4 v[162:165], v[98:99], off offset:192
	global_load_dwordx4 v[166:169], v[98:99], off offset:224
	global_load_dwordx4 v[170:173], v[240:241], off offset:-4096
	global_load_dwordx4 v[174:177], v[240:241], off offset:-4080
	global_load_dwordx4 v[194:197], v[240:241], off offset:-4064
	global_load_dwordx4 v[198:201], v[240:241], off offset:-4048
	global_load_dwordx4 v[202:205], v[98:99], off offset:256
	global_load_dwordx4 v[226:229], v[98:99], off offset:288
	global_load_dwordx4 v[230:233], v[98:99], off offset:320
	global_load_dwordx4 v[234:237], v[98:99], off offset:352
	s_add_i32 s64, s64, 1
	s_add_i32 s66, s66, 16
	s_waitcnt vmcnt(16)
	v_pk_fma_f32 v[2:3], v[2:3], v[120:121], v[102:103]
	v_pk_fma_f32 v[4:5], v[4:5], v[122:123], v[104:105]
	v_pk_fma_f32 v[6:7], v[6:7], v[124:125], v[108:109]
	v_pk_fma_f32 v[8:9], v[8:9], v[126:127], v[110:111]
	v_pk_fma_f32 v[10:11], v[10:11], v[128:129], v[112:113]
	v_pk_fma_f32 v[12:13], v[12:13], v[130:131], v[114:115]
	v_pk_fma_f32 v[14:15], v[14:15], v[132:133], v[116:117]
	v_pk_fma_f32 v[16:17], v[16:17], v[134:135], v[118:119]
	global_load_dwordx4 v[102:105], v[240:241], off
	global_load_dwordx4 v[108:111], v[240:241], off offset:16
	global_load_dwordx4 v[112:115], v[240:241], off offset:32
	global_load_dwordx4 v[116:119], v[240:241], off offset:48
	global_load_dwordx4 v[120:123], v[98:99], off offset:384
	global_load_dwordx4 v[124:127], v[98:99], off offset:416
	global_load_dwordx4 v[128:131], v[98:99], off offset:448
	global_load_dwordx4 v[132:135], v[98:99], off offset:480
	s_waitcnt vmcnt(16)
	v_pk_fma_f32 v[50:51], v[50:51], v[154:155], v[138:139]
	v_pk_fma_f32 v[52:53], v[52:53], v[156:157], v[140:141]
	v_pk_fma_f32 v[54:55], v[54:55], v[158:159], v[142:143]
	v_pk_fma_f32 v[56:57], v[56:57], v[160:161], v[144:145]
	v_pk_fma_f32 v[58:59], v[58:59], v[162:163], v[146:147]
	v_pk_fma_f32 v[60:61], v[60:61], v[164:165], v[148:149]
	v_pk_fma_f32 v[62:63], v[62:63], v[166:167], v[150:151]
	v_pk_fma_f32 v[64:65], v[64:65], v[168:169], v[152:153]
	s_waitcnt vmcnt(8)
	v_pk_fma_f32 v[34:35], v[34:35], v[202:203], v[170:171]
	v_pk_fma_f32 v[36:37], v[36:37], v[204:205], v[172:173]
	v_pk_fma_f32 v[38:39], v[38:39], v[226:227], v[174:175]
	v_pk_fma_f32 v[40:41], v[40:41], v[228:229], v[176:177]
	v_pk_fma_f32 v[42:43], v[42:43], v[230:231], v[194:195]
	v_pk_fma_f32 v[44:45], v[44:45], v[232:233], v[196:197]
	v_pk_fma_f32 v[46:47], v[46:47], v[234:235], v[198:199]
	v_pk_fma_f32 v[48:49], v[48:49], v[236:237], v[200:201]
	s_waitcnt vmcnt(0)
	v_pk_fma_f32 v[18:19], v[18:19], v[120:121], v[102:103]
	v_pk_fma_f32 v[20:21], v[20:21], v[122:123], v[104:105]
	v_pk_fma_f32 v[22:23], v[22:23], v[124:125], v[108:109]
	v_pk_fma_f32 v[24:25], v[24:25], v[126:127], v[110:111]
	v_pk_fma_f32 v[26:27], v[26:27], v[128:129], v[112:113]
	v_pk_fma_f32 v[28:29], v[28:29], v[130:131], v[114:115]
	v_pk_fma_f32 v[30:31], v[30:31], v[132:133], v[116:117]
	v_pk_fma_f32 v[32:33], v[32:33], v[134:135], v[118:119]
	s_cmp_eq_u32 s33, s64
	s_cbranch_scc0 .LBB0_963
	s_and_saveexec_b64 s[64:65], s[42:43]
	s_cbranch_execz .LBB0_966

.LBB0_1722:
	s_waitcnt vmcnt(0)
	s_waitcnt vmcnt(0)
	s_branch .LBB0_1774

.LBB0_2305:
	s_andn2_b64 vcc, exec, s[0:1]
	s_cbranch_vccnz .LBB0_2321
	s_add_i32 s0, 0, 0x24170
	v_mov_b32_e32 v2, s0
	ds_read_b32 v2, v2
	s_movk_i32 s0, 0xbff
	s_lshl_b32 s1, s64, 3
	v_cmp_lt_i32_e32 vcc, s0, v128
	s_waitcnt lgkmcnt(0)
	v_readfirstlane_b32 s0, v2
	s_add_i32 s37, s1, s0
	s_add_i32 s37, s37, -8
	s_ashr_i32 s0, s37, 31
	s_lshr_b32 s1, s0, 30
	s_add_i32 s1, s37, s1
	s_ashr_i32 s36, s1, 2
	s_and_b32 s58, s1, -4
	s_ashr_i32 s1, s1, 31
	s_lshr_b32 s1, s1, 27
	s_add_i32 s1, s36, s1
	s_lshr_b32 s0, s0, 25
	s_andn2_b32 s1, s1, 31
	s_add_i32 s0, s37, s0
	s_sub_i32 s67, s36, s1
	s_ashr_i32 s36, s0, 7
	s_and_saveexec_b64 s[0:1], vcc
	s_xor_b64 s[0:1], exec, s[0:1]
	s_lshl_b32 s63, s36, 12
	s_lshl_b32 s59, s67, 7
	s_or_saveexec_b64 s[0:1], s[0:1]
	s_sub_i32 s62, s37, s58
	v_mov_b32_e32 v2, s63
	v_mov_b32_e32 v3, s59
	s_xor_b64 exec, exec, s[0:1]
	s_cbranch_execz .LBB0_2314
	s_lshl_b32 s64, s36, 12
	s_lshl_b32 s36, s62, 6
	s_lshl_b32 s63, s67, 7
	s_ashr_i32 s37, s36, 31
	s_add_i32 s65, s63, 0xffffff80
	v_mov_b32_e32 v11, s37
	v_or_b32_e32 v10, s36, v115
	s_mov_b64 s[36:37], 0
	s_movk_i32 s66, 0x90
	s_movk_i32 s70, 0xc0
	s_movk_i32 s71, 0x9ff
	v_mov_b32_e32 v12, v128
	v_ashrrev_i32_e32 v13, 3, v128
	v_mad_u32_u24 v16, v13, s66, v114
	v_mad_u32_u24 v17, v13, s70, v114
	v_add_u32_e32 v17, 0xd800, v17
	v_add_u32_e32 v14, 0, v13
	v_add_u32_e32 v14, s65, v14
	v_cmp_lt_i32_e32 vcc, -1, v14
	v_mov_b32_e32 v20, 0
	v_mov_b32_e32 v21, 0
	v_mov_b32_e32 v22, 0
	v_mov_b32_e32 v23, 0
	v_mov_b32_e32 v24, 0
	v_mov_b32_e32 v25, 0
	v_mov_b32_e32 v26, 0
	v_mov_b32_e32 v27, 0
	s_and_saveexec_b64 s[58:59], vcc
	s_cbranch_execz .Lat_skip_0
	v_add_u32_e32 v2, s64, v14
	v_ashrrev_i32_e32 v3, 31, v2
	v_lshlrev_b64 v[2:3], 8, v[2:3]
	v_lshl_add_u64 v[2:3], v[2:3], 0, v[10:11]
	v_lshlrev_b64 v[2:3], 1, v[2:3]
	v_lshl_add_u64 v[4:5], s[56:57], 0, v[2:3]
	v_lshl_add_u64 v[2:3], s[48:49], 0, v[2:3]
	global_load_dwordx4 v[20:23], v[2:3], off
	global_load_dwordx4 v[24:27], v[4:5], off
.Lat_skip_0:
	s_or_b64 exec, exec, s[58:59]
	v_add_u32_e32 v14, 64, v13
	v_add_u32_e32 v14, s65, v14
	v_cmp_lt_i32_e32 vcc, -1, v14
	v_mov_b32_e32 v28, 0
	v_mov_b32_e32 v29, 0
	v_mov_b32_e32 v30, 0
	v_mov_b32_e32 v31, 0
	v_mov_b32_e32 v32, 0
	v_mov_b32_e32 v33, 0
	v_mov_b32_e32 v34, 0
	v_mov_b32_e32 v35, 0
	s_and_saveexec_b64 s[58:59], vcc
	s_cbranch_execz .Lat_skip_1
	v_add_u32_e32 v2, s64, v14
	v_ashrrev_i32_e32 v3, 31, v2
	v_lshlrev_b64 v[2:3], 8, v[2:3]
	v_lshl_add_u64 v[2:3], v[2:3], 0, v[10:11]
	v_lshlrev_b64 v[2:3], 1, v[2:3]
	v_lshl_add_u64 v[4:5], s[56:57], 0, v[2:3]
	v_lshl_add_u64 v[2:3], s[48:49], 0, v[2:3]
	global_load_dwordx4 v[28:31], v[2:3], off
	global_load_dwordx4 v[32:35], v[4:5], off
.Lat_skip_1:
	s_or_b64 exec, exec, s[58:59]
	v_add_u32_e32 v14, 128, v13
	v_add_u32_e32 v14, s65, v14
	v_cmp_lt_i32_e32 vcc, -1, v14
	v_mov_b32_e32 v36, 0
	v_mov_b32_e32 v37, 0
	v_mov_b32_e32 v38, 0
	v_mov_b32_e32 v39, 0
	v_mov_b32_e32 v40, 0
	v_mov_b32_e32 v41, 0
	v_mov_b32_e32 v42, 0
	v_mov_b32_e32 v43, 0
	s_and_saveexec_b64 s[58:59], vcc
	s_cbranch_execz .Lat_skip_2
	v_add_u32_e32 v2, s64, v14
	v_ashrrev_i32_e32 v3, 31, v2
	v_lshlrev_b64 v[2:3], 8, v[2:3]
	v_lshl_add_u64 v[2:3], v[2:3], 0, v[10:11]
	v_lshlrev_b64 v[2:3], 1, v[2:3]
	v_lshl_add_u64 v[4:5], s[56:57], 0, v[2:3]
	v_lshl_add_u64 v[2:3], s[48:49], 0, v[2:3]
	global_load_dwordx4 v[36:39], v[2:3], off
	global_load_dwordx4 v[40:43], v[4:5], off
.Lat_skip_2:
	s_or_b64 exec, exec, s[58:59]
	v_add_u32_e32 v14, 192, v13
	v_add_u32_e32 v14, s65, v14
	v_cmp_lt_i32_e32 vcc, -1, v14
	v_mov_b32_e32 v44, 0
	v_mov_b32_e32 v45, 0
	v_mov_b32_e32 v46, 0
	v_mov_b32_e32 v47, 0
	v_mov_b32_e32 v48, 0
	v_mov_b32_e32 v49, 0
	v_mov_b32_e32 v50, 0
	v_mov_b32_e32 v51, 0
	s_and_saveexec_b64 s[58:59], vcc
	s_cbranch_execz .Lat_skip_3
	v_add_u32_e32 v2, s64, v14
	v_ashrrev_i32_e32 v3, 31, v2
	v_lshlrev_b64 v[2:3], 8, v[2:3]
	v_lshl_add_u64 v[2:3], v[2:3], 0, v[10:11]
	v_lshlrev_b64 v[2:3], 1, v[2:3]
	v_lshl_add_u64 v[4:5], s[56:57], 0, v[2:3]
	v_lshl_add_u64 v[2:3], s[48:49], 0, v[2:3]
	global_load_dwordx4 v[44:47], v[2:3], off
	global_load_dwordx4 v[48:51], v[4:5], off
.Lat_skip_3:
	s_or_b64 exec, exec, s[58:59]
	v_add_u32_e32 v14, 256, v13
	v_add_u32_e32 v14, s65, v14
	v_cmp_lt_i32_e32 vcc, -1, v14
	v_mov_b32_e32 v52, 0
	v_mov_b32_e32 v53, 0
	v_mov_b32_e32 v54, 0
	v_mov_b32_e32 v55, 0
	v_mov_b32_e32 v56, 0
	v_mov_b32_e32 v57, 0
	v_mov_b32_e32 v58, 0
	v_mov_b32_e32 v59, 0
	s_and_saveexec_b64 s[58:59], vcc
	s_cbranch_execz .Lat_skip_4
	v_add_u32_e32 v2, s64, v14
	v_ashrrev_i32_e32 v3, 31, v2
	v_lshlrev_b64 v[2:3], 8, v[2:3]
	v_lshl_add_u64 v[2:3], v[2:3], 0, v[10:11]
	v_lshlrev_b64 v[2:3], 1, v[2:3]
	v_lshl_add_u64 v[4:5], s[56:57], 0, v[2:3]
	v_lshl_add_u64 v[2:3], s[48:49], 0, v[2:3]
	global_load_dwordx4 v[52:55], v[2:3], off
	global_load_dwordx4 v[56:59], v[4:5], off
.Lat_skip_4:
	s_or_b64 exec, exec, s[58:59]
	v_add_u32_e32 v14, 320, v13
	v_add_u32_e32 v14, s65, v14
	v_cmp_lt_i32_e32 vcc, -1, v14
	v_mov_b32_e32 v60, 0
	v_mov_b32_e32 v61, 0
	v_mov_b32_e32 v62, 0
	v_mov_b32_e32 v63, 0
	v_mov_b32_e32 v64, 0
	v_mov_b32_e32 v65, 0
	v_mov_b32_e32 v66, 0
	v_mov_b32_e32 v67, 0
	s_and_saveexec_b64 s[58:59], vcc
	s_cbranch_execz .Lat_skip_5
	v_add_u32_e32 v2, s64, v14
	v_ashrrev_i32_e32 v3, 31, v2
	v_lshlrev_b64 v[2:3], 8, v[2:3]
	v_lshl_add_u64 v[2:3], v[2:3], 0, v[10:11]
	v_lshlrev_b64 v[2:3], 1, v[2:3]
	v_lshl_add_u64 v[4:5], s[56:57], 0, v[2:3]
	v_lshl_add_u64 v[2:3], s[48:49], 0, v[2:3]
	global_load_dwordx4 v[60:63], v[2:3], off
	global_load_dwordx4 v[64:67], v[4:5], off
.Lat_skip_5:
	s_or_b64 exec, exec, s[58:59]
	s_waitcnt vmcnt(11)
	ds_write_b128 v16, v[20:23] offset:0
	s_waitcnt vmcnt(10)
	ds_write_b128 v17, v[24:27] offset:0
	s_waitcnt vmcnt(9)
	ds_write_b128 v16, v[28:31] offset:9216
	s_waitcnt vmcnt(8)
	ds_write_b128 v17, v[32:35] offset:12288
	s_waitcnt vmcnt(7)
	ds_write_b128 v16, v[36:39] offset:18432
	s_waitcnt vmcnt(6)
	ds_write_b128 v17, v[40:43] offset:24576
	s_waitcnt vmcnt(5)
	ds_write_b128 v16, v[44:47] offset:27648
	s_waitcnt vmcnt(4)
	ds_write_b128 v17, v[48:51] offset:36864
	s_waitcnt vmcnt(3)
	ds_write_b128 v16, v[52:55] offset:36864
	s_waitcnt vmcnt(2)
	ds_write_b128 v17, v[56:59] offset:49152
	s_waitcnt vmcnt(1)
	ds_write_b128 v16, v[60:63] offset:46080
	s_waitcnt vmcnt(0)
	ds_write_b128 v17, v[64:67] offset:61440
